# speedup vs baseline: 1.0056x; 1.0012x over previous
; DEV float4 ld_nt4(const float4* p) { const f32x4 v = __builtin_nontemporal_load((const f32x4*)p); return make_float4(v[0], v[1], v[2], v[3]); }
; DEV TrTile tr_tile(const Params& p, int l, int t) {
;     ...
;   if (t < n_in) { r.W = p.w_in + (size_t)l * DM * DIN; r.Wt = p.winT; r.K = DM; r.N = DIN; r.k0 = (t % 32) * 64; r.n0 = (t / 32) * 64; r.nout = r.n0; }
;   else if (t < n_in + n_out) { int q = t - n_in; r.W = p.w_out + (size_t)l * DM * DM; r.Wt = p.woutT; r.K = DM; r.N = DM; r.k0 = (q % 32) * 64; r.n0 = (q / 32) * 64; r.nout = r.n0; }
;   else if (t < n_in + n_out + n_up) {
;     int q = t - n_in - n_out; r.W = p.w_up + (size_t)l * DM * DFF2; r.Wt = p.wupT; r.K = DM; r.N = DFF2; r.k0 = (q % 32) * 64; r.n0 = (q / 32) * 64;
;     r.nout = (r.n0 < DFF) ? ((r.n0 >> 7) * 256 + (r.n0 & 127)) : ((((r.n0 - DFF) >> 7) * 256) + 128 + ((r.n0 - DFF) & 127));
;   } else { int q = t - n_in - n_out - n_up; r.W = p.w_down + (size_t)l * DFF * DM; r.Wt = p.wdownT; r.K = DFF; r.N = DM; r.k0 = (q % 88) * 64; r.n0 = (q / 88) * 64; r.nout = r.n0; }
; DEV void phase_convert(const Params& p, int l, unsigned char* smem) {
;     ...
;     for (int j = 0; j < 4; ++j) {
;       const TrTile tt = tr_tile(p, l, g * 4 + j);
;       float* tile = tiles + j * 64 * 65;
; #pragma unroll
;       for (int i = 0; i < 2; ++i) {
;         const int e = tid + i * NT, r = e >> 4, c4 = (e & 15) * 4;
;         const float4 v = ld_nt4((const float4*)(tt.W + (size_t)(tt.k0 + r) * tt.N + tt.n0 + c4));
;         tile[r * 65 + c4 + 0] = v.x; tile[r * 65 + c4 + 1] = v.y; tile[r * 65 + c4 + 2] = v.z; tile[r * 65 + c4 + 3] = v.w;
.LBB0_37:
	s_ashr_i32 s5, s4, 31
	s_lshl_b64 s[4:5], s[4:5], 2
	s_add_u32 s0, s0, s4
	v_add_u32_e32 v35, s12, v6
	s_addc_u32 s1, s1, s5
	v_ashrrev_i32_e32 v36, 31, v35
	v_lshl_add_u64 v[40:41], s[0:1], 0, v[2:3]
	v_mul_lo_u32 v38, s6, v36
	v_mul_lo_u32 v39, s7, v35
	v_mad_u64_u32 v[36:37], s[0:1], s6, v35, 0
	v_add_u32_e32 v35, s12, v7
	v_add3_u32 v37, v37, v38, v39
	v_ashrrev_i32_e32 v42, 31, v35
	v_lshl_add_u64 v[36:37], v[36:37], 2, v[40:41]
	v_mul_lo_u32 v44, s6, v42
	v_mul_lo_u32 v45, s7, v35
	v_mad_u64_u32 v[42:43], s[0:1], s6, v35, 0
	global_load_dwordx4 v[200:203], v[36:37], off nt
	v_add3_u32 v43, v43, v44, v45
	v_lshl_add_u64 v[40:41], v[42:43], 2, v[40:41]
	global_load_dwordx4 v[204:207], v[40:41], off nt
	s_add_i32 s39, s30, 1
	s_cmpk_gt_i32 s39, 0x9ff
	s_cselect_b64 s[6:7], -1, 0
	s_cmpk_lt_i32 s39, 0xa00
	s_cbranch_scc1 .LBB0_41
	s_cmpk_lt_u32 s30, 0xe00
	s_cbranch_scc1 .LBB0_42
	s_cmpk_lt_u32 s30, 0x2400
	s_cbranch_scc1 .LBB0_43
	s_add_i32 s0, s39, 0xdc00
	s_and_b32 s1, s0, 0xffff
	s_mul_i32 s1, s1, 0xba2f
	s_lshr_b32 s4, s1, 16
	s_lshr_b32 s1, s1, 22
	s_mulk_i32 s1, 0x58
	s_sub_i32 s0, s0, s1
	v_readlane_b32 s48, v253, 22
	s_lshl_b32 s0, s0, 6
	v_readlane_b32 s56, v253, 30
	v_readlane_b32 s57, v253, 31
	s_and_b32 s14, s0, 0xffc0
	s_and_b32 s4, s4, 0xffc0
	s_mov_b64 s[0:1], s[56:57]
	v_readlane_b32 s49, v253, 23
	v_readlane_b32 s50, v253, 24
	v_readlane_b32 s51, v253, 25
	v_readlane_b32 s52, v253, 26
	v_readlane_b32 s53, v253, 27
	v_readlane_b32 s54, v253, 28
	v_readlane_b32 s55, v253, 29
	v_readlane_b32 s58, v253, 32
	v_readlane_b32 s59, v253, 33
	v_readlane_b32 s60, v253, 34
	v_readlane_b32 s61, v253, 35
	v_readlane_b32 s62, v253, 36
	v_readlane_b32 s63, v253, 37
	s_mov_b64 s[10:11], 0x800
	s_cbranch_execz .LBB0_44
	s_branch .LBB0_45

; DEV float4 ld_nt4(const float4* p) { const f32x4 v = __builtin_nontemporal_load((const f32x4*)p); return make_float4(v[0], v[1], v[2], v[3]); }
; DEV TrTile tr_tile(const Params& p, int l, int t) {
;     ...
;   if (t < n_in) { r.W = p.w_in + (size_t)l * DM * DIN; r.Wt = p.winT; r.K = DM; r.N = DIN; r.k0 = (t % 32) * 64; r.n0 = (t / 32) * 64; r.nout = r.n0; }
;   else if (t < n_in + n_out) { int q = t - n_in; r.W = p.w_out + (size_t)l * DM * DM; r.Wt = p.woutT; r.K = DM; r.N = DM; r.k0 = (q % 32) * 64; r.n0 = (q / 32) * 64; r.nout = r.n0; }
;   else if (t < n_in + n_out + n_up) {
;     int q = t - n_in - n_out; r.W = p.w_up + (size_t)l * DM * DFF2; r.Wt = p.wupT; r.K = DM; r.N = DFF2; r.k0 = (q % 32) * 64; r.n0 = (q / 32) * 64;
;     r.nout = (r.n0 < DFF) ? ((r.n0 >> 7) * 256 + (r.n0 & 127)) : ((((r.n0 - DFF) >> 7) * 256) + 128 + ((r.n0 - DFF) & 127));
;   } else { int q = t - n_in - n_out - n_up; r.W = p.w_down + (size_t)l * DFF * DM; r.Wt = p.wdownT; r.K = DFF; r.N = DM; r.k0 = (q % 88) * 64; r.n0 = (q / 88) * 64; r.nout = r.n0; }
; DEV void phase_convert(const Params& p, int l, unsigned char* smem) {
;     ...
;     for (int j = 0; j < 4; ++j) {
;       const TrTile tt = tr_tile(p, l, g * 4 + j);
;       float* tile = tiles + j * 64 * 65;
; #pragma unroll
;       for (int i = 0; i < 2; ++i) {
;         const int e = tid + i * NT, r = e >> 4, c4 = (e & 15) * 4;
;         const float4 v = ld_nt4((const float4*)(tt.W + (size_t)(tt.k0 + r) * tt.N + tt.n0 + c4));
;         tile[r * 65 + c4 + 0] = v.x; tile[r * 65 + c4 + 1] = v.y; tile[r * 65 + c4 + 2] = v.z; tile[r * 65 + c4 + 3] = v.w;
.LBB0_49:
	s_ashr_i32 s5, s4, 31
	s_lshl_b64 s[4:5], s[4:5], 2
	s_add_u32 s0, s0, s4
	v_add_u32_e32 v35, s14, v6
	s_addc_u32 s1, s1, s5
	v_ashrrev_i32_e32 v36, 31, v35
	v_lshl_add_u64 v[40:41], s[0:1], 0, v[2:3]
	v_mul_lo_u32 v38, s10, v36
	v_mul_lo_u32 v39, s11, v35
	v_mad_u64_u32 v[36:37], s[0:1], s10, v35, 0
	v_add_u32_e32 v35, s14, v7
	v_add3_u32 v37, v37, v38, v39
	v_ashrrev_i32_e32 v42, 31, v35
	v_lshl_add_u64 v[36:37], v[36:37], 2, v[40:41]
	v_mul_lo_u32 v44, s10, v42
	v_mul_lo_u32 v45, s11, v35
	v_mad_u64_u32 v[42:43], s[0:1], s10, v35, 0
	global_load_dwordx4 v[208:211], v[36:37], off nt
	v_add3_u32 v43, v43, v44, v45
	v_lshl_add_u64 v[40:41], v[42:43], 2, v[40:41]
	global_load_dwordx4 v[212:215], v[40:41], off nt
	s_add_i32 s38, s30, 2
	s_cmpk_gt_i32 s38, 0x9ff
	s_cselect_b64 s[4:5], -1, 0
	s_cmpk_lt_i32 s38, 0xa00
	s_cbranch_scc1 .LBB0_53
	s_cmpk_lt_u32 s30, 0xe00
	s_cbranch_scc1 .LBB0_54
	s_cmpk_lt_u32 s30, 0x2400
	s_cbranch_scc1 .LBB0_55
	s_add_i32 s0, s38, 0xdc00
	s_and_b32 s1, s0, 0xffff
	s_mul_i32 s1, s1, 0xba2f
	s_lshr_b32 s10, s1, 16
	s_lshr_b32 s1, s1, 22
	s_mulk_i32 s1, 0x58
	s_sub_i32 s0, s0, s1
	v_readlane_b32 s48, v253, 22
	s_lshl_b32 s0, s0, 6
	v_readlane_b32 s56, v253, 30
	v_readlane_b32 s57, v253, 31
	s_and_b32 s16, s0, 0xffc0
	s_and_b32 s10, s10, 0xffc0
	s_mov_b64 s[0:1], s[56:57]
	v_readlane_b32 s49, v253, 23
	v_readlane_b32 s50, v253, 24
	v_readlane_b32 s51, v253, 25
	v_readlane_b32 s52, v253, 26
	v_readlane_b32 s53, v253, 27
	v_readlane_b32 s54, v253, 28
	v_readlane_b32 s55, v253, 29
	v_readlane_b32 s58, v253, 32
	v_readlane_b32 s59, v253, 33
	v_readlane_b32 s60, v253, 34
	v_readlane_b32 s61, v253, 35
	v_readlane_b32 s62, v253, 36
	v_readlane_b32 s63, v253, 37
	s_mov_b64 s[12:13], 0x800
	s_cbranch_execz .LBB0_56
	s_branch .LBB0_57

; DEV float4 ld_nt4(const float4* p) { const f32x4 v = __builtin_nontemporal_load((const f32x4*)p); return make_float4(v[0], v[1], v[2], v[3]); }
; DEV TrTile tr_tile(const Params& p, int l, int t) {
;     ...
;   if (t < n_in) { r.W = p.w_in + (size_t)l * DM * DIN; r.Wt = p.winT; r.K = DM; r.N = DIN; r.k0 = (t % 32) * 64; r.n0 = (t / 32) * 64; r.nout = r.n0; }
;   else if (t < n_in + n_out) { int q = t - n_in; r.W = p.w_out + (size_t)l * DM * DM; r.Wt = p.woutT; r.K = DM; r.N = DM; r.k0 = (q % 32) * 64; r.n0 = (q / 32) * 64; r.nout = r.n0; }
;   else if (t < n_in + n_out + n_up) {
;     int q = t - n_in - n_out; r.W = p.w_up + (size_t)l * DM * DFF2; r.Wt = p.wupT; r.K = DM; r.N = DFF2; r.k0 = (q % 32) * 64; r.n0 = (q / 32) * 64;
;     r.nout = (r.n0 < DFF) ? ((r.n0 >> 7) * 256 + (r.n0 & 127)) : ((((r.n0 - DFF) >> 7) * 256) + 128 + ((r.n0 - DFF) & 127));
;   } else { int q = t - n_in - n_out - n_up; r.W = p.w_down + (size_t)l * DFF * DM; r.Wt = p.wdownT; r.K = DFF; r.N = DM; r.k0 = (q % 88) * 64; r.n0 = (q / 88) * 64; r.nout = r.n0; }
; DEV void phase_convert(const Params& p, int l, unsigned char* smem) {
;     ...
;     for (int j = 0; j < 4; ++j) {
;       const TrTile tt = tr_tile(p, l, g * 4 + j);
;       float* tile = tiles + j * 64 * 65;
; #pragma unroll
;       for (int i = 0; i < 2; ++i) {
;         const int e = tid + i * NT, r = e >> 4, c4 = (e & 15) * 4;
;         const float4 v = ld_nt4((const float4*)(tt.W + (size_t)(tt.k0 + r) * tt.N + tt.n0 + c4));
;         tile[r * 65 + c4 + 0] = v.x; tile[r * 65 + c4 + 1] = v.y; tile[r * 65 + c4 + 2] = v.z; tile[r * 65 + c4 + 3] = v.w;
.LBB0_61:
	s_ashr_i32 s11, s10, 31
	s_lshl_b64 s[10:11], s[10:11], 2
	s_add_u32 s0, s0, s10
	v_add_u32_e32 v35, s16, v6
	s_addc_u32 s1, s1, s11
	v_ashrrev_i32_e32 v36, 31, v35
	v_lshl_add_u64 v[40:41], s[0:1], 0, v[2:3]
	v_mul_lo_u32 v38, s12, v36
	v_mul_lo_u32 v39, s13, v35
	v_mad_u64_u32 v[36:37], s[0:1], s12, v35, 0
	v_add_u32_e32 v35, s16, v7
	v_add3_u32 v37, v37, v38, v39
	v_ashrrev_i32_e32 v42, 31, v35
	v_lshl_add_u64 v[36:37], v[36:37], 2, v[40:41]
	v_mul_lo_u32 v44, s12, v42
	v_mul_lo_u32 v45, s13, v35
	v_mad_u64_u32 v[42:43], s[0:1], s12, v35, 0
	global_load_dwordx4 v[216:219], v[36:37], off nt
	v_add3_u32 v43, v43, v44, v45
	v_lshl_add_u64 v[40:41], v[42:43], 2, v[40:41]
	global_load_dwordx4 v[220:223], v[40:41], off nt
	s_add_i32 s37, s30, 3
	s_cmpk_gt_i32 s37, 0x9ff
	s_cselect_b64 s[0:1], -1, 0
	s_cmpk_lt_i32 s37, 0xa00
	s_cbranch_scc1 .LBB0_65
	s_cmpk_lt_u32 s30, 0xe00
	s_cbranch_scc1 .LBB0_66
	s_cmpk_lt_u32 s30, 0x2400
	s_cbranch_scc1 .LBB0_67
	s_add_i32 s10, s37, 0xdc00
	s_and_b32 s11, s10, 0xffff
	s_mul_i32 s11, s11, 0xba2f
	s_lshr_b32 s12, s11, 16
	s_lshr_b32 s11, s11, 22
	s_mulk_i32 s11, 0x58
	s_sub_i32 s10, s10, s11
	v_readlane_b32 s48, v253, 22
	s_lshl_b32 s10, s10, 6
	v_readlane_b32 s56, v253, 30
	v_readlane_b32 s57, v253, 31
	s_and_b32 s42, s10, 0xffc0
	s_and_b32 s14, s12, 0xffc0
	s_mov_b64 s[10:11], s[56:57]
	v_readlane_b32 s49, v253, 23
	v_readlane_b32 s50, v253, 24
	v_readlane_b32 s51, v253, 25
	v_readlane_b32 s52, v253, 26
	v_readlane_b32 s53, v253, 27
	v_readlane_b32 s54, v253, 28
	v_readlane_b32 s55, v253, 29
	v_readlane_b32 s58, v253, 32
	v_readlane_b32 s59, v253, 33
	v_readlane_b32 s60, v253, 34
	v_readlane_b32 s61, v253, 35
	v_readlane_b32 s62, v253, 36
	v_readlane_b32 s63, v253, 37
	s_mov_b64 s[12:13], 0x800
	s_cbranch_execz .LBB0_68
	s_branch .LBB0_69

; DEV float4 ld_nt4(const float4* p) { const f32x4 v = __builtin_nontemporal_load((const f32x4*)p); return make_float4(v[0], v[1], v[2], v[3]); }
; DEV void phase_convert(const Params& p, int l, unsigned char* smem) {
;     ...
;     for (int j = 0; j < 4; ++j) {
;       const TrTile tt = tr_tile(p, l, g * 4 + j);
;       float* tile = tiles + j * 64 * 65;
; #pragma unroll
;       for (int i = 0; i < 2; ++i) {
;         const int e = tid + i * NT, r = e >> 4, c4 = (e & 15) * 4;
;         const float4 v = ld_nt4((const float4*)(tt.W + (size_t)(tt.k0 + r) * tt.N + tt.n0 + c4));
;         tile[r * 65 + c4 + 0] = v.x; tile[r * 65 + c4 + 1] = v.y; tile[r * 65 + c4 + 2] = v.z; tile[r * 65 + c4 + 3] = v.w;
;       }
;     }
;     __syncthreads();
.LBB0_73:
	s_ashr_i32 s15, s14, 31
	s_lshl_b64 s[14:15], s[14:15], 2
	s_add_u32 s10, s10, s14
	v_add_u32_e32 v35, s42, v6
	s_addc_u32 s11, s11, s15
	v_ashrrev_i32_e32 v36, 31, v35
	v_lshl_add_u64 v[40:41], s[10:11], 0, v[2:3]
	v_mul_lo_u32 v38, s12, v36
	v_mul_lo_u32 v39, s13, v35
	v_mad_u64_u32 v[36:37], s[10:11], s12, v35, 0
	v_add3_u32 v37, v37, v38, v39
	v_lshl_add_u64 v[36:37], v[36:37], 2, v[40:41]
	global_load_dwordx4 v[224:227], v[36:37], off nt
	v_add_u32_e32 v35, s42, v7
	s_and_b64 vcc, exec, s[8:9]
	v_ashrrev_i32_e32 v36, 31, v35
	v_mul_lo_u32 v38, s12, v36
	v_mul_lo_u32 v39, s13, v35
	v_mad_u64_u32 v[36:37], s[10:11], s12, v35, 0
	v_add3_u32 v37, v37, v38, v39
	v_lshl_add_u64 v[36:37], v[36:37], 2, v[40:41]
	global_load_dwordx4 v[228:231], v[36:37], off nt
	s_waitcnt lgkmcnt(0)
	s_waitcnt vmcnt(7)
	ds_write2_b32 v9, v200, v201 offset1:1
	ds_write2_b32 v9, v202, v203 offset0:2 offset1:3
	s_waitcnt vmcnt(6)
	ds_write2_b32 v10, v204, v205 offset1:1
	ds_write2_b32 v10, v206, v207 offset0:2 offset1:3
	s_waitcnt vmcnt(5)
	ds_write2_b32 v11, v208, v209 offset1:1
	ds_write2_b32 v12, v210, v211 offset1:1
	s_waitcnt vmcnt(4)
	ds_write2_b32 v13, v212, v213 offset1:1
	ds_write2_b32 v14, v214, v215 offset1:1
	s_waitcnt vmcnt(3)
	ds_write2_b32 v15, v216, v217 offset1:1
	ds_write2_b32 v16, v218, v219 offset1:1
	s_waitcnt vmcnt(2)
	ds_write2_b32 v17, v220, v221 offset1:1
	ds_write2_b32 v18, v222, v223 offset1:1
	s_waitcnt vmcnt(1)
	ds_write2_b32 v19, v224, v225 offset1:1
	ds_write2_b32 v20, v226, v227 offset1:1
	s_waitcnt vmcnt(0)
	ds_write2_b32 v21, v228, v229 offset1:1
	ds_write2_b32 v22, v230, v231 offset1:1
	s_barrier
	s_cbranch_vccz .LBB0_84
	s_cmpk_gt_u32 s30, 0xdff
	s_cbranch_scc0 .LBB0_85
	s_cmpk_gt_u32 s30, 0x23ff
	s_mov_b64 s[12:13], -1
	s_cbranch_scc0 .LBB0_77
	s_add_i32 s8, s30, 0xdc00
	s_and_b32 s9, s8, 0xffff
	s_mul_i32 s9, s9, 0xba2f
	s_lshr_b32 s10, s9, 16
	s_lshr_b32 s9, s9, 22
	s_mulk_i32 s9, 0x58
	s_sub_i32 s8, s8, s9
	s_lshl_b32 s8, s8, 6
	s_and_b32 s8, s8, 0xffc0
	s_and_b32 s16, s10, 0xffc0
	s_mov_b64 s[12:13], 0
	s_mov_b64 s[10:11], s[70:71]

; DEV float4 ld_nt4(const float4* p) { const f32x4 v = __builtin_nontemporal_load((const f32x4*)p); return make_float4(v[0], v[1], v[2], v[3]); }
; DEV TrTile tr_tile(const Params& p, int l, int t) {
;     ...
;   if (t < n_in) { r.W = p.w_in + (size_t)l * DM * DIN; r.Wt = p.winT; r.K = DM; r.N = DIN; r.k0 = (t % 32) * 64; r.n0 = (t / 32) * 64; r.nout = r.n0; }
;   else if (t < n_in + n_out) { int q = t - n_in; r.W = p.w_out + (size_t)l * DM * DM; r.Wt = p.woutT; r.K = DM; r.N = DM; r.k0 = (q % 32) * 64; r.n0 = (q / 32) * 64; r.nout = r.n0; }
;   else if (t < n_in + n_out + n_up) {
;     int q = t - n_in - n_out; r.W = p.w_up + (size_t)l * DM * DFF2; r.Wt = p.wupT; r.K = DM; r.N = DFF2; r.k0 = (q % 32) * 64; r.n0 = (q / 32) * 64;
;     r.nout = (r.n0 < DFF) ? ((r.n0 >> 7) * 256 + (r.n0 & 127)) : ((((r.n0 - DFF) >> 7) * 256) + 128 + ((r.n0 - DFF) & 127));
;   } else { int q = t - n_in - n_out - n_up; r.W = p.w_down + (size_t)l * DFF * DM; r.Wt = p.wdownT; r.K = DFF; r.N = DM; r.k0 = (q % 88) * 64; r.n0 = (q / 88) * 64; r.nout = r.n0; }
; DEV void phase_convert(const Params& p, int l, unsigned char* smem) {
;     ...
;     for (int j = 0; j < 4; ++j) {
;       const TrTile tt = tr_tile(p, l, g * 4 + j);
;       float* tile = tiles + j * 64 * 65;
; #pragma unroll
;       for (int i = 0; i < 2; ++i) {
;         const int e = tid + i * NT, r = e >> 4, c4 = (e & 15) * 4;
;         const float4 v = ld_nt4((const float4*)(tt.W + (size_t)(tt.k0 + r) * tt.N + tt.n0 + c4));
;         tile[r * 65 + c4 + 0] = v.x; tile[r * 65 + c4 + 1] = v.y; tile[r * 65 + c4 + 2] = v.z; tile[r * 65 + c4 + 3] = v.w;
.LBB0_196:
	s_ashr_i32 s5, s4, 31
	s_lshl_b64 s[4:5], s[4:5], 2
	s_add_u32 s4, s10, s4
	v_add_u32_e32 v9, s34, v4
	s_addc_u32 s5, s11, s5
	v_ashrrev_i32_e32 v10, 31, v9
	v_lshl_add_u64 v[2:3], s[4:5], 0, v[128:129]
	v_mul_lo_u32 v12, s0, v10
	v_mul_lo_u32 v13, s1, v9
	v_mad_u64_u32 v[10:11], s[4:5], s0, v9, 0
	v_add3_u32 v11, v11, v12, v13
	v_lshl_add_u64 v[10:11], v[10:11], 2, v[2:3]
	global_load_dwordx4 v[200:203], v[10:11], off nt
	v_add_u32_e32 v9, s34, v5
	s_add_i32 s48, s18, 1
	s_cmpk_gt_i32 s48, 0x9ff
	s_mov_b64 s[34:35], -1
	s_cselect_b64 s[10:11], -1, 0
	s_cmpk_lt_i32 s48, 0xa00
	v_ashrrev_i32_e32 v10, 31, v9
	v_mul_lo_u32 v12, s0, v10
	v_mul_lo_u32 v13, s1, v9
	v_mad_u64_u32 v[10:11], s[0:1], s0, v9, 0
	v_add3_u32 v11, v11, v12, v13
	v_lshl_add_u64 v[2:3], v[10:11], 2, v[2:3]
	global_load_dwordx4 v[204:207], v[2:3], off nt
	s_cbranch_scc1 .LBB0_206
	s_cmpk_lt_u32 s18, 0xe00
	s_cbranch_scc1 .LBB0_203
	s_cmpk_lt_u32 s18, 0x2400
	s_mov_b64 s[14:15], -1
	s_cbranch_scc1 .LBB0_200
	s_add_i32 s0, s48, 0xdc00
	s_and_b32 s1, s0, 0xffff
	s_mul_i32 s1, s1, 0xba2f
	s_lshr_b32 s4, s1, 16
	s_lshr_b32 s1, s1, 22
	s_mulk_i32 s1, 0x58
	s_sub_i32 s0, s0, s1
	s_lshl_b32 s0, s0, 6
	s_and_b32 s41, s0, 0xffc0
	s_and_b32 s4, s4, 0xffc0
	s_mov_b64 s[14:15], 0

; DEV float4 ld_nt4(const float4* p) { const f32x4 v = __builtin_nontemporal_load((const f32x4*)p); return make_float4(v[0], v[1], v[2], v[3]); }
; DEV TrTile tr_tile(const Params& p, int l, int t) {
;     ...
;   if (t < n_in) { r.W = p.w_in + (size_t)l * DM * DIN; r.Wt = p.winT; r.K = DM; r.N = DIN; r.k0 = (t % 32) * 64; r.n0 = (t / 32) * 64; r.nout = r.n0; }
;   else if (t < n_in + n_out) { int q = t - n_in; r.W = p.w_out + (size_t)l * DM * DM; r.Wt = p.woutT; r.K = DM; r.N = DM; r.k0 = (q % 32) * 64; r.n0 = (q / 32) * 64; r.nout = r.n0; }
;   else if (t < n_in + n_out + n_up) {
;     int q = t - n_in - n_out; r.W = p.w_up + (size_t)l * DM * DFF2; r.Wt = p.wupT; r.K = DM; r.N = DFF2; r.k0 = (q % 32) * 64; r.n0 = (q / 32) * 64;
;     r.nout = (r.n0 < DFF) ? ((r.n0 >> 7) * 256 + (r.n0 & 127)) : ((((r.n0 - DFF) >> 7) * 256) + 128 + ((r.n0 - DFF) & 127));
;   } else { int q = t - n_in - n_out - n_up; r.W = p.w_down + (size_t)l * DFF * DM; r.Wt = p.wdownT; r.K = DFF; r.N = DM; r.k0 = (q % 88) * 64; r.n0 = (q / 88) * 64; r.nout = r.n0; }
; DEV void phase_convert(const Params& p, int l, unsigned char* smem) {
;     ...
;     for (int j = 0; j < 4; ++j) {
;       const TrTile tt = tr_tile(p, l, g * 4 + j);
;       float* tile = tiles + j * 64 * 65;
; #pragma unroll
;       for (int i = 0; i < 2; ++i) {
;         const int e = tid + i * NT, r = e >> 4, c4 = (e & 15) * 4;
;         const float4 v = ld_nt4((const float4*)(tt.W + (size_t)(tt.k0 + r) * tt.N + tt.n0 + c4));
;         tile[r * 65 + c4 + 0] = v.x; tile[r * 65 + c4 + 1] = v.y; tile[r * 65 + c4 + 2] = v.z; tile[r * 65 + c4 + 3] = v.w;
.LBB0_208:
	s_ashr_i32 s5, s4, 31
	s_lshl_b64 s[4:5], s[4:5], 2
	s_add_u32 s4, s14, s4
	v_add_u32_e32 v9, s41, v4
	s_addc_u32 s5, s15, s5
	v_ashrrev_i32_e32 v10, 31, v9
	v_lshl_add_u64 v[2:3], s[4:5], 0, v[128:129]
	v_mul_lo_u32 v12, s0, v10
	v_mul_lo_u32 v13, s1, v9
	v_mad_u64_u32 v[10:11], s[4:5], s0, v9, 0
	v_add3_u32 v11, v11, v12, v13
	v_lshl_add_u64 v[10:11], v[10:11], 2, v[2:3]
	global_load_dwordx4 v[208:211], v[10:11], off nt
	v_add_u32_e32 v9, 0x4100, v7
	s_add_i32 s47, s18, 2
	s_cmpk_gt_i32 s47, 0x9ff
	s_mov_b64 s[34:35], -1
	s_cselect_b64 s[4:5], -1, 0
	s_cmpk_lt_i32 s47, 0xa00
	v_add_u32_e32 v9, 0x4108, v7
	v_add_u32_e32 v9, s41, v5
	v_ashrrev_i32_e32 v10, 31, v9
	v_mul_lo_u32 v12, s0, v10
	v_mul_lo_u32 v13, s1, v9
	v_mad_u64_u32 v[10:11], s[0:1], s0, v9, 0
	v_add3_u32 v11, v11, v12, v13
	v_lshl_add_u64 v[2:3], v[10:11], 2, v[2:3]
	global_load_dwordx4 v[212:215], v[2:3], off nt
	v_add_u32_e32 v2, 0x4100, v8
	v_add_u32_e32 v2, 0x4108, v8
	s_cbranch_scc1 .LBB0_218
	s_cmpk_lt_u32 s18, 0xe00
	s_cbranch_scc1 .LBB0_215
	s_cmpk_lt_u32 s18, 0x2400
	s_cbranch_scc1 .LBB0_212
	s_add_i32 s0, s47, 0xdc00
	s_and_b32 s1, s0, 0xffff
	s_mul_i32 s1, s1, 0xba2f
	s_lshr_b32 s14, s1, 16
	s_lshr_b32 s1, s1, 22
	s_mulk_i32 s1, 0x58
	s_sub_i32 s0, s0, s1
	s_lshl_b32 s0, s0, 6
	s_and_b32 s41, s0, 0xffc0
	s_and_b32 s14, s14, 0xffc0
	s_mov_b64 s[34:35], 0

; DEV float4 ld_nt4(const float4* p) { const f32x4 v = __builtin_nontemporal_load((const f32x4*)p); return make_float4(v[0], v[1], v[2], v[3]); }
; DEV TrTile tr_tile(const Params& p, int l, int t) {
;     ...
;   if (t < n_in) { r.W = p.w_in + (size_t)l * DM * DIN; r.Wt = p.winT; r.K = DM; r.N = DIN; r.k0 = (t % 32) * 64; r.n0 = (t / 32) * 64; r.nout = r.n0; }
;   else if (t < n_in + n_out) { int q = t - n_in; r.W = p.w_out + (size_t)l * DM * DM; r.Wt = p.woutT; r.K = DM; r.N = DM; r.k0 = (q % 32) * 64; r.n0 = (q / 32) * 64; r.nout = r.n0; }
;   else if (t < n_in + n_out + n_up) {
;     int q = t - n_in - n_out; r.W = p.w_up + (size_t)l * DM * DFF2; r.Wt = p.wupT; r.K = DM; r.N = DFF2; r.k0 = (q % 32) * 64; r.n0 = (q / 32) * 64;
;     r.nout = (r.n0 < DFF) ? ((r.n0 >> 7) * 256 + (r.n0 & 127)) : ((((r.n0 - DFF) >> 7) * 256) + 128 + ((r.n0 - DFF) & 127));
;   } else { int q = t - n_in - n_out - n_up; r.W = p.w_down + (size_t)l * DFF * DM; r.Wt = p.wdownT; r.K = DFF; r.N = DM; r.k0 = (q % 88) * 64; r.n0 = (q / 88) * 64; r.nout = r.n0; }
; DEV void phase_convert(const Params& p, int l, unsigned char* smem) {
;     ...
;     for (int j = 0; j < 4; ++j) {
;       const TrTile tt = tr_tile(p, l, g * 4 + j);
;       float* tile = tiles + j * 64 * 65;
; #pragma unroll
;       for (int i = 0; i < 2; ++i) {
;         const int e = tid + i * NT, r = e >> 4, c4 = (e & 15) * 4;
;         const float4 v = ld_nt4((const float4*)(tt.W + (size_t)(tt.k0 + r) * tt.N + tt.n0 + c4));
;         tile[r * 65 + c4 + 0] = v.x; tile[r * 65 + c4 + 1] = v.y; tile[r * 65 + c4 + 2] = v.z; tile[r * 65 + c4 + 3] = v.w;
.LBB0_220:
	s_ashr_i32 s15, s14, 31
	s_lshl_b64 s[14:15], s[14:15], 2
	s_add_u32 s14, s92, s14
	v_add_u32_e32 v9, s41, v4
	s_addc_u32 s15, s93, s15
	v_ashrrev_i32_e32 v10, 31, v9
	v_lshl_add_u64 v[2:3], s[14:15], 0, v[128:129]
	v_mul_lo_u32 v12, s0, v10
	v_mul_lo_u32 v13, s1, v9
	v_mad_u64_u32 v[10:11], s[14:15], s0, v9, 0
	v_add3_u32 v11, v11, v12, v13
	v_lshl_add_u64 v[10:11], v[10:11], 2, v[2:3]
	global_load_dwordx4 v[216:219], v[10:11], off nt
	v_add_u32_e32 v9, 0x8200, v7
	s_mov_b64 vcc, -1
	v_add_u32_e32 v9, 0x8208, v7
	v_add_u32_e32 v9, s41, v5
	v_ashrrev_i32_e32 v10, 31, v9
	v_mul_lo_u32 v12, s0, v10
	v_mul_lo_u32 v13, s1, v9
	v_mad_u64_u32 v[10:11], s[0:1], s0, v9, 0
	v_add3_u32 v11, v11, v12, v13
	v_lshl_add_u64 v[2:3], v[10:11], 2, v[2:3]
	global_load_dwordx4 v[220:223], v[2:3], off nt
	s_add_i32 s41, s18, 3
	v_add_u32_e32 v2, 0x8200, v8
	s_cmpk_gt_i32 s41, 0x9ff
	s_cselect_b64 s[0:1], -1, 0
	s_cmpk_lt_i32 s41, 0xa00
	v_add_u32_e32 v2, 0x8208, v8
	s_cbranch_scc1 .LBB0_230
	s_cmpk_lt_u32 s18, 0xe00
	s_cbranch_scc1 .LBB0_227
	s_cmpk_lt_u32 s18, 0x2400
	s_mov_b64 s[34:35], -1
	s_cbranch_scc1 .LBB0_224
	s_add_i32 s14, s41, 0xdc00
	s_and_b32 s15, s14, 0xffff
	s_mul_i32 s15, s15, 0xba2f
	s_lshr_b32 s34, s15, 16
	s_lshr_b32 s15, s15, 22
	s_mulk_i32 s15, 0x58
	s_sub_i32 s14, s14, s15
	s_lshl_b32 s14, s14, 6
	s_and_b32 s50, s14, 0xffc0
	s_and_b32 s92, s34, 0xffc0
	s_mov_b64 s[34:35], 0

; DEV float4 ld_nt4(const float4* p) { const f32x4 v = __builtin_nontemporal_load((const f32x4*)p); return make_float4(v[0], v[1], v[2], v[3]); }
; DEV void phase_convert(const Params& p, int l, unsigned char* smem) {
;     ...
;     for (int j = 0; j < 4; ++j) {
;       const TrTile tt = tr_tile(p, l, g * 4 + j);
;       float* tile = tiles + j * 64 * 65;
; #pragma unroll
;       for (int i = 0; i < 2; ++i) {
;         const int e = tid + i * NT, r = e >> 4, c4 = (e & 15) * 4;
;         const float4 v = ld_nt4((const float4*)(tt.W + (size_t)(tt.k0 + r) * tt.N + tt.n0 + c4));
;         tile[r * 65 + c4 + 0] = v.x; tile[r * 65 + c4 + 1] = v.y; tile[r * 65 + c4 + 2] = v.z; tile[r * 65 + c4 + 3] = v.w;
;       }
;     }
;     __syncthreads();
.LBB0_232:
	s_ashr_i32 s93, s92, 31
	s_lshl_b64 s[52:53], s[92:93], 2
	s_add_u32 s34, s34, s52
	v_add_u32_e32 v9, s50, v4
	s_addc_u32 s35, s35, s53
	v_ashrrev_i32_e32 v10, 31, v9
	v_lshl_add_u64 v[2:3], s[34:35], 0, v[128:129]
	v_mul_lo_u32 v12, s14, v10
	v_mul_lo_u32 v13, s15, v9
	v_mad_u64_u32 v[10:11], s[34:35], s14, v9, 0
	v_add3_u32 v11, v11, v12, v13
	v_lshl_add_u64 v[10:11], v[10:11], 2, v[2:3]
	global_load_dwordx4 v[224:227], v[10:11], off nt
	v_add_u32_e32 v9, 0xc300, v7
	s_and_b64 vcc, exec, s[12:13]
	v_add_u32_e32 v9, 0xc308, v7
	v_add_u32_e32 v9, s50, v5
	v_ashrrev_i32_e32 v10, 31, v9
	v_mul_lo_u32 v12, s14, v10
	v_mul_lo_u32 v13, s15, v9
	v_mad_u64_u32 v[10:11], s[14:15], s14, v9, 0
	v_add3_u32 v11, v11, v12, v13
	v_lshl_add_u64 v[2:3], v[10:11], 2, v[2:3]
	global_load_dwordx4 v[228:231], v[2:3], off nt
	v_add_u32_e32 v2, 0xc300, v8
	v_add_u32_e32 v2, 0xc308, v8
	s_waitcnt lgkmcnt(0)
	s_waitcnt vmcnt(7)
	ds_write2_b32 v7, v200, v201 offset1:1
	ds_write2_b32 v7, v202, v203 offset0:2 offset1:3
	s_waitcnt vmcnt(6)
	ds_write2_b32 v8, v204, v205 offset1:1
	ds_write2_b32 v8, v206, v207 offset0:2 offset1:3
	s_waitcnt vmcnt(5)
	v_add_u32_e32 v232, 0x4100, v7
	ds_write2_b32 v232, v208, v209 offset1:1
	v_add_u32_e32 v232, 0x4108, v7
	ds_write2_b32 v232, v210, v211 offset1:1
	s_waitcnt vmcnt(4)
	v_add_u32_e32 v232, 0x4100, v8
	ds_write2_b32 v232, v212, v213 offset1:1
	v_add_u32_e32 v232, 0x4108, v8
	ds_write2_b32 v232, v214, v215 offset1:1
	s_waitcnt vmcnt(3)
	v_add_u32_e32 v232, 0x8200, v7
	ds_write2_b32 v232, v216, v217 offset1:1
	v_add_u32_e32 v232, 0x8208, v7
	ds_write2_b32 v232, v218, v219 offset1:1
	s_waitcnt vmcnt(2)
	v_add_u32_e32 v232, 0x8200, v8
	ds_write2_b32 v232, v220, v221 offset1:1
	v_add_u32_e32 v232, 0x8208, v8
	ds_write2_b32 v232, v222, v223 offset1:1
	s_waitcnt vmcnt(1)
	v_add_u32_e32 v232, 0xc300, v7
	ds_write2_b32 v232, v224, v225 offset1:1
	v_add_u32_e32 v232, 0xc308, v7
	ds_write2_b32 v232, v226, v227 offset1:1
	s_waitcnt vmcnt(0)
	v_add_u32_e32 v232, 0xc300, v8
	ds_write2_b32 v232, v228, v229 offset1:1
	v_add_u32_e32 v232, 0xc308, v8
	ds_write2_b32 v232, v230, v231 offset1:1
	s_barrier
	s_cbranch_vccz .LBB0_243
	s_cmpk_gt_u32 s18, 0xdff
	s_cbranch_scc0 .LBB0_244
	s_cmpk_gt_u32 s18, 0x23ff
	s_mov_b64 s[34:35], -1
	s_cbranch_scc0 .LBB0_236
	s_add_i32 s12, s18, 0xdc00
	s_and_b32 s13, s12, 0xffff
	s_mul_i32 s13, s13, 0xba2f
	s_lshr_b32 s14, s13, 16
	s_lshr_b32 s13, s13, 22
	s_mulk_i32 s13, 0x58
	s_sub_i32 s12, s12, s13
	s_lshl_b32 s12, s12, 6
	s_and_b32 s12, s12, 0xffc0
	s_and_b32 s50, s14, 0xffc0
	s_mov_b64 s[34:35], 0
	s_mov_b64 s[14:15], s[70:71]

; DEV float4 ld_nt4(const float4* p) { const f32x4 v = __builtin_nontemporal_load((const f32x4*)p); return make_float4(v[0], v[1], v[2], v[3]); }
; DEV TrTile tr_tile(const Params& p, int l, int t) {
;     ...
;   if (t < n_in) { r.W = p.w_in + (size_t)l * DM * DIN; r.Wt = p.winT; r.K = DM; r.N = DIN; r.k0 = (t % 32) * 64; r.n0 = (t / 32) * 64; r.nout = r.n0; }
;   else if (t < n_in + n_out) { int q = t - n_in; r.W = p.w_out + (size_t)l * DM * DM; r.Wt = p.woutT; r.K = DM; r.N = DM; r.k0 = (q % 32) * 64; r.n0 = (q / 32) * 64; r.nout = r.n0; }
;   else if (t < n_in + n_out + n_up) {
;     int q = t - n_in - n_out; r.W = p.w_up + (size_t)l * DM * DFF2; r.Wt = p.wupT; r.K = DM; r.N = DFF2; r.k0 = (q % 32) * 64; r.n0 = (q / 32) * 64;
;     r.nout = (r.n0 < DFF) ? ((r.n0 >> 7) * 256 + (r.n0 & 127)) : ((((r.n0 - DFF) >> 7) * 256) + 128 + ((r.n0 - DFF) & 127));
;   } else { int q = t - n_in - n_out - n_up; r.W = p.w_down + (size_t)l * DFF * DM; r.Wt = p.wdownT; r.K = DFF; r.N = DM; r.k0 = (q % 88) * 64; r.n0 = (q / 88) * 64; r.nout = r.n0; }
; DEV void phase_convert(const Params& p, int l, unsigned char* smem) {
;     ...
;     for (int j = 0; j < 4; ++j) {
;       const TrTile tt = tr_tile(p, l, g * 4 + j);
;       float* tile = tiles + j * 64 * 65;
; #pragma unroll
;       for (int i = 0; i < 2; ++i) {
;         const int e = tid + i * NT, r = e >> 4, c4 = (e & 15) * 4;
;         const float4 v = ld_nt4((const float4*)(tt.W + (size_t)(tt.k0 + r) * tt.N + tt.n0 + c4));
;         tile[r * 65 + c4 + 0] = v.x; tile[r * 65 + c4 + 1] = v.y; tile[r * 65 + c4 + 2] = v.z; tile[r * 65 + c4 + 3] = v.w;
.LBB0_516:
	s_ashr_i32 s5, s4, 31
	s_lshl_b64 s[4:5], s[4:5], 2
	s_add_u32 s0, s0, s4
	v_add_u32_e32 v9, s12, v4
	s_addc_u32 s1, s1, s5
	v_ashrrev_i32_e32 v10, 31, v9
	v_lshl_add_u64 v[2:3], s[0:1], 0, v[128:129]
	v_mul_lo_u32 v12, s2, v10
	v_mul_lo_u32 v13, s3, v9
	v_mad_u64_u32 v[10:11], s[0:1], s2, v9, 0
	v_add3_u32 v11, v11, v12, v13
	v_lshl_add_u64 v[10:11], v[10:11], 2, v[2:3]
	global_load_dwordx4 v[200:203], v[10:11], off nt
	v_add_u32_e32 v9, s12, v5
	s_add_i32 s45, s18, 1
	s_cmpk_gt_i32 s45, 0x9ff
	s_cselect_b64 s[4:5], -1, 0
	s_cmpk_lt_i32 s45, 0xa00
	v_ashrrev_i32_e32 v10, 31, v9
	v_mul_lo_u32 v12, s2, v10
	v_mul_lo_u32 v13, s3, v9
	v_mad_u64_u32 v[10:11], s[0:1], s2, v9, 0
	v_add3_u32 v11, v11, v12, v13
	v_lshl_add_u64 v[2:3], v[10:11], 2, v[2:3]
	global_load_dwordx4 v[204:207], v[2:3], off nt
	s_cbranch_scc1 .LBB0_520
	s_cmpk_lt_u32 s18, 0xe00
	s_cbranch_scc1 .LBB0_521
	s_cmpk_lt_u32 s18, 0x2400
	s_cbranch_scc1 .LBB0_522
	s_add_i32 s0, s45, 0xdc00
	s_and_b32 s1, s0, 0xffff
	s_mul_i32 s1, s1, 0xba2f
	s_lshr_b32 s2, s1, 16
	s_lshr_b32 s1, s1, 22
	s_mulk_i32 s1, 0x58
	s_sub_i32 s0, s0, s1
	v_readlane_b32 s48, v253, 22
	s_lshl_b32 s0, s0, 6
	v_readlane_b32 s56, v253, 30
	v_readlane_b32 s57, v253, 31
	s_and_b32 s14, s0, 0xffc0
	s_and_b32 s10, s2, 0xffc0
	s_mov_b64 s[2:3], s[56:57]
	v_readlane_b32 s49, v253, 23
	v_readlane_b32 s50, v253, 24
	v_readlane_b32 s51, v253, 25
	v_readlane_b32 s52, v253, 26
	v_readlane_b32 s53, v253, 27
	v_readlane_b32 s54, v253, 28
	v_readlane_b32 s55, v253, 29
	v_readlane_b32 s58, v253, 32
	v_readlane_b32 s59, v253, 33
	v_readlane_b32 s60, v253, 34
	v_readlane_b32 s61, v253, 35
	v_readlane_b32 s62, v253, 36
	v_readlane_b32 s63, v253, 37
	s_mov_b64 s[0:1], 0x800
	s_cbranch_execz .LBB0_523
	s_branch .LBB0_524

; DEV float4 ld_nt4(const float4* p) { const f32x4 v = __builtin_nontemporal_load((const f32x4*)p); return make_float4(v[0], v[1], v[2], v[3]); }
; DEV TrTile tr_tile(const Params& p, int l, int t) {
;     ...
;   if (t < n_in) { r.W = p.w_in + (size_t)l * DM * DIN; r.Wt = p.winT; r.K = DM; r.N = DIN; r.k0 = (t % 32) * 64; r.n0 = (t / 32) * 64; r.nout = r.n0; }
;   else if (t < n_in + n_out) { int q = t - n_in; r.W = p.w_out + (size_t)l * DM * DM; r.Wt = p.woutT; r.K = DM; r.N = DM; r.k0 = (q % 32) * 64; r.n0 = (q / 32) * 64; r.nout = r.n0; }
;   else if (t < n_in + n_out + n_up) {
;     int q = t - n_in - n_out; r.W = p.w_up + (size_t)l * DM * DFF2; r.Wt = p.wupT; r.K = DM; r.N = DFF2; r.k0 = (q % 32) * 64; r.n0 = (q / 32) * 64;
;     r.nout = (r.n0 < DFF) ? ((r.n0 >> 7) * 256 + (r.n0 & 127)) : ((((r.n0 - DFF) >> 7) * 256) + 128 + ((r.n0 - DFF) & 127));
;   } else { int q = t - n_in - n_out - n_up; r.W = p.w_down + (size_t)l * DFF * DM; r.Wt = p.wdownT; r.K = DFF; r.N = DM; r.k0 = (q % 88) * 64; r.n0 = (q / 88) * 64; r.nout = r.n0; }
; DEV void phase_convert(const Params& p, int l, unsigned char* smem) {
;     ...
;     for (int j = 0; j < 4; ++j) {
;       const TrTile tt = tr_tile(p, l, g * 4 + j);
;       float* tile = tiles + j * 64 * 65;
; #pragma unroll
;       for (int i = 0; i < 2; ++i) {
;         const int e = tid + i * NT, r = e >> 4, c4 = (e & 15) * 4;
;         const float4 v = ld_nt4((const float4*)(tt.W + (size_t)(tt.k0 + r) * tt.N + tt.n0 + c4));
;         tile[r * 65 + c4 + 0] = v.x; tile[r * 65 + c4 + 1] = v.y; tile[r * 65 + c4 + 2] = v.z; tile[r * 65 + c4 + 3] = v.w;
.LBB0_528:
	s_ashr_i32 s11, s10, 31
	s_lshl_b64 s[10:11], s[10:11], 2
	s_add_u32 s2, s2, s10
	v_add_u32_e32 v9, s14, v4
	s_addc_u32 s3, s3, s11
	v_ashrrev_i32_e32 v10, 31, v9
	v_lshl_add_u64 v[2:3], s[2:3], 0, v[128:129]
	v_mul_lo_u32 v12, s0, v10
	v_mul_lo_u32 v13, s1, v9
	v_mad_u64_u32 v[10:11], s[2:3], s0, v9, 0
	v_add3_u32 v11, v11, v12, v13
	v_lshl_add_u64 v[10:11], v[10:11], 2, v[2:3]
	global_load_dwordx4 v[208:211], v[10:11], off nt
	v_add_u32_e32 v9, 0x4100, v7
	s_add_i32 s44, s18, 2
	s_cmpk_gt_i32 s44, 0x9ff
	s_cselect_b64 s[2:3], -1, 0
	s_cmpk_lt_i32 s44, 0xa00
	v_add_u32_e32 v9, 0x4108, v7
	v_add_u32_e32 v9, s14, v5
	v_ashrrev_i32_e32 v10, 31, v9
	v_mul_lo_u32 v12, s0, v10
	v_mul_lo_u32 v13, s1, v9
	v_mad_u64_u32 v[10:11], s[0:1], s0, v9, 0
	v_add3_u32 v11, v11, v12, v13
	v_lshl_add_u64 v[2:3], v[10:11], 2, v[2:3]
	global_load_dwordx4 v[212:215], v[2:3], off nt
	v_add_u32_e32 v2, 0x4100, v8
	v_add_u32_e32 v2, 0x4108, v8
	s_cbranch_scc1 .LBB0_532
	s_cmpk_lt_u32 s18, 0xe00
	s_cbranch_scc1 .LBB0_533
	s_cmpk_lt_u32 s18, 0x2400
	s_cbranch_scc1 .LBB0_534
	s_add_i32 s0, s44, 0xdc00
	s_and_b32 s1, s0, 0xffff
	s_mul_i32 s1, s1, 0xba2f
	s_lshr_b32 s10, s1, 16
	s_lshr_b32 s1, s1, 22
	s_mulk_i32 s1, 0x58
	s_sub_i32 s0, s0, s1
	v_readlane_b32 s48, v253, 22
	s_lshl_b32 s0, s0, 6
	v_readlane_b32 s56, v253, 30
	v_readlane_b32 s57, v253, 31
	s_and_b32 s16, s0, 0xffc0
	s_and_b32 s12, s10, 0xffc0
	s_mov_b64 s[10:11], s[56:57]
	v_readlane_b32 s49, v253, 23
	v_readlane_b32 s50, v253, 24
	v_readlane_b32 s51, v253, 25
	v_readlane_b32 s52, v253, 26
	v_readlane_b32 s53, v253, 27
	v_readlane_b32 s54, v253, 28
	v_readlane_b32 s55, v253, 29
	v_readlane_b32 s58, v253, 32
	v_readlane_b32 s59, v253, 33
	v_readlane_b32 s60, v253, 34
	v_readlane_b32 s61, v253, 35
	v_readlane_b32 s62, v253, 36
	v_readlane_b32 s63, v253, 37
	s_mov_b64 s[0:1], 0x800
	s_cbranch_execz .LBB0_535
	s_branch .LBB0_536

; DEV float4 ld_nt4(const float4* p) { const f32x4 v = __builtin_nontemporal_load((const f32x4*)p); return make_float4(v[0], v[1], v[2], v[3]); }
; DEV TrTile tr_tile(const Params& p, int l, int t) {
;     ...
;   if (t < n_in) { r.W = p.w_in + (size_t)l * DM * DIN; r.Wt = p.winT; r.K = DM; r.N = DIN; r.k0 = (t % 32) * 64; r.n0 = (t / 32) * 64; r.nout = r.n0; }
;   else if (t < n_in + n_out) { int q = t - n_in; r.W = p.w_out + (size_t)l * DM * DM; r.Wt = p.woutT; r.K = DM; r.N = DM; r.k0 = (q % 32) * 64; r.n0 = (q / 32) * 64; r.nout = r.n0; }
;   else if (t < n_in + n_out + n_up) {
;     int q = t - n_in - n_out; r.W = p.w_up + (size_t)l * DM * DFF2; r.Wt = p.wupT; r.K = DM; r.N = DFF2; r.k0 = (q % 32) * 64; r.n0 = (q / 32) * 64;
;     r.nout = (r.n0 < DFF) ? ((r.n0 >> 7) * 256 + (r.n0 & 127)) : ((((r.n0 - DFF) >> 7) * 256) + 128 + ((r.n0 - DFF) & 127));
;   } else { int q = t - n_in - n_out - n_up; r.W = p.w_down + (size_t)l * DFF * DM; r.Wt = p.wdownT; r.K = DFF; r.N = DM; r.k0 = (q % 88) * 64; r.n0 = (q / 88) * 64; r.nout = r.n0; }
; DEV void phase_convert(const Params& p, int l, unsigned char* smem) {
;     ...
;     for (int j = 0; j < 4; ++j) {
;       const TrTile tt = tr_tile(p, l, g * 4 + j);
;       float* tile = tiles + j * 64 * 65;
; #pragma unroll
;       for (int i = 0; i < 2; ++i) {
;         const int e = tid + i * NT, r = e >> 4, c4 = (e & 15) * 4;
;         const float4 v = ld_nt4((const float4*)(tt.W + (size_t)(tt.k0 + r) * tt.N + tt.n0 + c4));
;         tile[r * 65 + c4 + 0] = v.x; tile[r * 65 + c4 + 1] = v.y; tile[r * 65 + c4 + 2] = v.z; tile[r * 65 + c4 + 3] = v.w;
.LBB0_540:
	s_ashr_i32 s13, s12, 31
	s_lshl_b64 s[12:13], s[12:13], 2
	s_add_u32 s10, s10, s12
	v_add_u32_e32 v9, s16, v4
	s_addc_u32 s11, s11, s13
	v_ashrrev_i32_e32 v10, 31, v9
	v_lshl_add_u64 v[2:3], s[10:11], 0, v[128:129]
	v_mul_lo_u32 v12, s0, v10
	v_mul_lo_u32 v13, s1, v9
	v_mad_u64_u32 v[10:11], s[10:11], s0, v9, 0
	v_add3_u32 v11, v11, v12, v13
	v_lshl_add_u64 v[10:11], v[10:11], 2, v[2:3]
	global_load_dwordx4 v[216:219], v[10:11], off nt
	v_add_u32_e32 v9, 0x8200, v7
	s_add_i32 s41, s18, 3
	s_cmpk_gt_i32 s41, 0x9ff
	v_add_u32_e32 v9, 0x8208, v7
	v_add_u32_e32 v9, s16, v5
	v_ashrrev_i32_e32 v10, 31, v9
	v_mul_lo_u32 v12, s0, v10
	v_mul_lo_u32 v13, s1, v9
	v_mad_u64_u32 v[10:11], s[0:1], s0, v9, 0
	v_add3_u32 v11, v11, v12, v13
	v_lshl_add_u64 v[2:3], v[10:11], 2, v[2:3]
	global_load_dwordx4 v[220:223], v[2:3], off nt
	v_add_u32_e32 v2, 0x8200, v8
	s_cselect_b64 s[0:1], -1, 0
	s_cmpk_lt_i32 s41, 0xa00
	v_add_u32_e32 v2, 0x8208, v8
	s_cbranch_scc1 .LBB0_544
	s_cmpk_lt_u32 s18, 0xe00
	s_cbranch_scc1 .LBB0_545
	s_cmpk_lt_u32 s18, 0x2400
	s_cbranch_scc1 .LBB0_546
	s_add_i32 s10, s41, 0xdc00
	s_and_b32 s11, s10, 0xffff
	s_mul_i32 s11, s11, 0xba2f
	s_lshr_b32 s12, s11, 16
	s_lshr_b32 s11, s11, 22
	s_mulk_i32 s11, 0x58
	s_sub_i32 s10, s10, s11
	v_readlane_b32 s48, v253, 22
	s_lshl_b32 s10, s10, 6
	v_readlane_b32 s56, v253, 30
	v_readlane_b32 s57, v253, 31
	s_and_b32 s47, s10, 0xffc0
	s_and_b32 s14, s12, 0xffc0
	s_mov_b64 s[12:13], s[56:57]
	v_readlane_b32 s49, v253, 23
	v_readlane_b32 s50, v253, 24
	v_readlane_b32 s51, v253, 25
	v_readlane_b32 s52, v253, 26
	v_readlane_b32 s53, v253, 27
	v_readlane_b32 s54, v253, 28
	v_readlane_b32 s55, v253, 29
	v_readlane_b32 s58, v253, 32
	v_readlane_b32 s59, v253, 33
	v_readlane_b32 s60, v253, 34
	v_readlane_b32 s61, v253, 35
	v_readlane_b32 s62, v253, 36
	v_readlane_b32 s63, v253, 37
	s_mov_b64 s[10:11], 0x800
	s_cbranch_execz .LBB0_547
	s_branch .LBB0_548

; DEV float4 ld_nt4(const float4* p) { const f32x4 v = __builtin_nontemporal_load((const f32x4*)p); return make_float4(v[0], v[1], v[2], v[3]); }
; DEV void phase_convert(const Params& p, int l, unsigned char* smem) {
;     ...
;     for (int j = 0; j < 4; ++j) {
;       const TrTile tt = tr_tile(p, l, g * 4 + j);
;       float* tile = tiles + j * 64 * 65;
; #pragma unroll
;       for (int i = 0; i < 2; ++i) {
;         const int e = tid + i * NT, r = e >> 4, c4 = (e & 15) * 4;
;         const float4 v = ld_nt4((const float4*)(tt.W + (size_t)(tt.k0 + r) * tt.N + tt.n0 + c4));
;         tile[r * 65 + c4 + 0] = v.x; tile[r * 65 + c4 + 1] = v.y; tile[r * 65 + c4 + 2] = v.z; tile[r * 65 + c4 + 3] = v.w;
;       }
;     }
;     __syncthreads();
.LBB0_552:
	s_ashr_i32 s15, s14, 31
	s_lshl_b64 s[14:15], s[14:15], 2
	s_add_u32 s12, s12, s14
	v_add_u32_e32 v9, s47, v4
	s_addc_u32 s13, s13, s15
	v_ashrrev_i32_e32 v10, 31, v9
	v_lshl_add_u64 v[2:3], s[12:13], 0, v[128:129]
	v_mul_lo_u32 v12, s10, v10
	v_mul_lo_u32 v13, s11, v9
	v_mad_u64_u32 v[10:11], s[12:13], s10, v9, 0
	v_add3_u32 v11, v11, v12, v13
	v_lshl_add_u64 v[10:11], v[10:11], 2, v[2:3]
	global_load_dwordx4 v[224:227], v[10:11], off nt
	v_add_u32_e32 v9, 0xc300, v7
	s_and_b64 vcc, exec, s[6:7]
	v_add_u32_e32 v9, 0xc308, v7
	v_add_u32_e32 v9, s47, v5
	v_ashrrev_i32_e32 v10, 31, v9
	v_mul_lo_u32 v12, s10, v10
	v_mul_lo_u32 v13, s11, v9
	v_mad_u64_u32 v[10:11], s[10:11], s10, v9, 0
	v_add3_u32 v11, v11, v12, v13
	v_lshl_add_u64 v[2:3], v[10:11], 2, v[2:3]
	global_load_dwordx4 v[228:231], v[2:3], off nt
	v_add_u32_e32 v2, 0xc300, v8
	v_add_u32_e32 v2, 0xc308, v8
	s_waitcnt lgkmcnt(0)
	s_waitcnt vmcnt(7)
	ds_write2_b32 v7, v200, v201 offset1:1
	ds_write2_b32 v7, v202, v203 offset0:2 offset1:3
	s_waitcnt vmcnt(6)
	ds_write2_b32 v8, v204, v205 offset1:1
	ds_write2_b32 v8, v206, v207 offset0:2 offset1:3
	s_waitcnt vmcnt(5)
	v_add_u32_e32 v232, 0x4100, v7
	ds_write2_b32 v232, v208, v209 offset1:1
	v_add_u32_e32 v232, 0x4108, v7
	ds_write2_b32 v232, v210, v211 offset1:1
	s_waitcnt vmcnt(4)
	v_add_u32_e32 v232, 0x4100, v8
	ds_write2_b32 v232, v212, v213 offset1:1
	v_add_u32_e32 v232, 0x4108, v8
	ds_write2_b32 v232, v214, v215 offset1:1
	s_waitcnt vmcnt(3)
	v_add_u32_e32 v232, 0x8200, v7
	ds_write2_b32 v232, v216, v217 offset1:1
	v_add_u32_e32 v232, 0x8208, v7
	ds_write2_b32 v232, v218, v219 offset1:1
	s_waitcnt vmcnt(2)
	v_add_u32_e32 v232, 0x8200, v8
	ds_write2_b32 v232, v220, v221 offset1:1
	v_add_u32_e32 v232, 0x8208, v8
	ds_write2_b32 v232, v222, v223 offset1:1
	s_waitcnt vmcnt(1)
	v_add_u32_e32 v232, 0xc300, v7
	ds_write2_b32 v232, v224, v225 offset1:1
	v_add_u32_e32 v232, 0xc308, v7
	ds_write2_b32 v232, v226, v227 offset1:1
	s_waitcnt vmcnt(0)
	v_add_u32_e32 v232, 0xc300, v8
	ds_write2_b32 v232, v228, v229 offset1:1
	v_add_u32_e32 v232, 0xc308, v8
	ds_write2_b32 v232, v230, v231 offset1:1
	s_barrier
	s_cbranch_vccz .LBB0_563
	s_cmpk_gt_u32 s18, 0xdff
	s_cbranch_scc0 .LBB0_564
	s_cmpk_gt_u32 s18, 0x23ff
	s_mov_b64 s[12:13], -1
	s_cbranch_scc0 .LBB0_556
	s_add_i32 s6, s18, 0xdc00
	s_and_b32 s7, s6, 0xffff
	s_mul_i32 s7, s7, 0xba2f
	s_lshr_b32 s10, s7, 16
	s_lshr_b32 s7, s7, 22
	s_mulk_i32 s7, 0x58
	s_sub_i32 s6, s6, s7
	s_lshl_b32 s6, s6, 6
	s_and_b32 s6, s6, 0xffc0
	s_and_b32 s16, s10, 0xffc0
	s_mov_b64 s[12:13], 0
	s_mov_b64 s[10:11], s[70:71]
